# T1: grid barrier - pollers watch the TOP counter itself (TOP >= (gen+1)*nx) instead of the second-stage TOPGEN flag, removing one atomic round trip from the barrier tail; on top of X1
# baseline (speedup 1.0000x reference)
.LBB0_595:
	s_or_b64 exec, exec, s[4:5]
	v_cvt_f32_u32_e32 v4, v2
	s_waitcnt vmcnt(0)
	v_readfirstlane_b32 s4, v3
	v_sub_u32_e32 v3, 0, v2
	v_rcp_iflag_f32_e32 v4, v4
	v_add_u32_e32 v5, s4, v1
	v_mul_f32_e32 v4, 0x4f7ffffe, v4
	v_cvt_u32_f32_e32 v4, v4
	v_mul_lo_u32 v1, v3, v4
	v_mul_hi_u32 v1, v4, v1
	v_add_u32_e32 v1, v4, v1
	v_mul_hi_u32 v1, v5, v1
	v_mul_lo_u32 v3, v1, v2
	v_sub_u32_e32 v3, v5, v3
	v_add_u32_e32 v4, 1, v1
	v_cmp_ge_u32_e32 vcc, v3, v2
	s_nop 1
	v_cndmask_b32_e32 v1, v1, v4, vcc
	v_sub_u32_e32 v4, v3, v2
	v_cndmask_b32_e32 v3, v3, v4, vcc
	v_add_u32_e32 v4, 1, v1
	v_cmp_ge_u32_e32 vcc, v3, v2
	v_add_u32_e32 v3, 1, v5
	s_nop 0
	v_cndmask_b32_e32 v1, v1, v4, vcc
	v_mul_lo_u32 v4, v2, v1
	v_add_u32_e32 v2, v4, v2
	v_cmp_ne_u32_e32 vcc, v3, v2
	s_and_saveexec_b64 s[4:5], vcc
	s_xor_b64 s[4:5], exec, s[4:5]
	s_cbranch_execz .LBB0_609
	v_readlane_b32 s6, v254, 40
	v_readlane_b32 s7, v254, 41
	s_waitcnt lgkmcnt(0)
	v_add_u32_e32 v6, 1, v1
	v_mul_lo_u32 v6, v6, v0
	s_nop 3
	global_load_dword v0, v81, s[6:7] sc1
	s_waitcnt vmcnt(0)
	v_cmp_lt_u32_e32 vcc, v0, v6
	s_and_saveexec_b64 s[6:7], vcc
	s_cbranch_execz .LBB0_608
	s_mov_b64 s[26:27], s[22:23]
	s_mov_b32 s18, 1
	s_mov_b64 s[8:9], 0
	s_branch .LBB0_599

.LBB0_603:
	v_readlane_b32 s14, v254, 40
	v_readlane_b32 s15, v254, 41
	s_add_i32 s18, s18, 1
	s_mov_b64 s[16:17], -1
	s_nop 2
	global_load_dword v0, v81, s[14:15] sc1
	s_waitcnt vmcnt(0)
	v_cmp_ge_u32_e32 vcc, v0, v6
	s_orn2_b64 s[14:15], vcc, exec
	s_branch .LBB0_598

.LBB0_612:
	s_or_b64 exec, exec, s[6:7]
	s_waitcnt vmcnt(0)
	v_readfirstlane_b32 s4, v2
	v_cvt_f32_u32_e32 v2, v0
	v_sub_u32_e32 v3, 0, v0
	v_add_u32_e32 v1, s4, v1
	v_readlane_b32 s4, v254, 42
	v_rcp_iflag_f32_e32 v2, v2
	v_readlane_b32 s5, v254, 43
	s_mov_b64 s[6:7], -1
	v_mul_f32_e32 v2, 0x4f7ffffe, v2
	v_cvt_u32_f32_e32 v2, v2
	v_mul_lo_u32 v3, v3, v2
	v_mul_hi_u32 v3, v2, v3
	v_add_u32_e32 v2, v2, v3
	v_mul_hi_u32 v2, v1, v2
	v_mul_lo_u32 v3, v2, v0
	v_sub_u32_e32 v3, v1, v3
	v_cmp_ge_u32_e32 vcc, v3, v0
	v_add_u32_e32 v4, 1, v2
	v_add_u32_e32 v1, 1, v1
	v_cndmask_b32_e32 v2, v2, v4, vcc
	v_sub_u32_e32 v4, v3, v0
	v_cndmask_b32_e32 v3, v3, v4, vcc
	v_cmp_ge_u32_e32 vcc, v3, v0
	v_add_u32_e32 v3, 1, v2
	s_nop 0
	v_cndmask_b32_e32 v2, v2, v3, vcc
	v_mul_lo_u32 v3, v0, v2
	v_add_u32_e32 v0, v3, v0
	v_cmp_ne_u32_e32 vcc, v1, v0
	v_mov_b32_e32 v6, v0
	v_mov_b64_e32 v[0:1], s[4:5]
	s_and_saveexec_b64 s[4:5], vcc
	s_cbranch_execz .LBB0_624
	v_readlane_b32 s6, v254, 40
	v_readlane_b32 s7, v254, 41
	s_mov_b64 s[8:9], 0
	s_nop 3
	global_load_dword v0, v81, s[6:7] sc1
	s_waitcnt vmcnt(0)
	v_cmp_lt_u32_e32 vcc, v0, v6
	s_and_saveexec_b64 s[6:7], vcc
	s_cbranch_execz .LBB0_623
	s_mov_b64 s[26:27], s[22:23]
	s_mov_b32 s18, 1
	s_branch .LBB0_616
